# scan: consumer output stores widened to 16 B/lane via v_permlane16_swap (one store instead of two), loader waves 2-3 issue the duplicate decay DMA with one lane
# speedup vs baseline: 1.0208x; 1.0019x over previous
; __device__ void scan_chain(const Params& p, int l, int chain, int vhalf, LAS unsigned char* lds) {
;     ...
;             LAS unsigned char* st = lds + (s % NSTAGE) * ST_BYTES;
;             bf16x8 qf[4][2], kf[8]; f32x4 dv[8];
; #pragma unroll
;             for (int kb = 0; kb < 4; ++kb)
; #pragma unroll
;                 for (int mt = 0; mt < 2; ++mt) {
;                     qf[kb][mt] = *(const LAS bf16x8*)(st + ST_Q + (16 * mt + l15) * 256 + (((4 * kb + q4) ^ l15) * 16));
;                 }
;             const bf16x8 vf = *(const LAS bf16x8*)(st + ST_V + (16 * w + l15) * 64 + ((q4 ^ swz) * 16));
;             u32x2 oi[2];
; #pragma unroll
;             for (int mt = 0; mt < 2; ++mt) { const int tr = 16 * mt + l15; oi[mt] = *(const LAS u32x2*)(st + ST_O + tr * 128 + (((2 * w + (q4 >> 1)) ^ (tr & 7)) * 16) + (q4 & 1) * 8); }
; #pragma unroll
;             for (int j = 0; j < 8; ++j) { dv[j] = *(const LAS f32x4*)(st + ST_D + (16 * j + 4 * q4) * 4); kf[j] = *(const LAS bf16x8*)(st + ST_K + (16 * j + l15) * 64 + ((q4 ^ swz) * 16)); }
;             __builtin_amdgcn_sched_barrier(0);
;             f32x4 o[2]; o[0] = (f32x4){0.f, 0.f, 0.f, 0.f}; o[1] = o[0];
; #pragma unroll
;             for (int kb = 0; kb < 4; ++kb) {
;                 u32x4 sb; sb.x = pk_bf16(S[2 * kb][0], S[2 * kb][1]); sb.y = pk_bf16(S[2 * kb][2], S[2 * kb][3]); sb.z = pk_bf16(S[2 * kb + 1][0], S[2 * kb + 1][1]); sb.w = pk_bf16(S[2 * kb + 1][2], S[2 * kb + 1][3]);
;                 const bf16x8 sfr = __builtin_bit_cast(bf16x8, sb);
;                 o[0] = __builtin_amdgcn_mfma_f32_16x16x32_bf16(sfr, qf[kb][0], o[0], 0, 0, 0);
;                 o[1] = __builtin_amdgcn_mfma_f32_16x16x32_bf16(sfr, qf[kb][1], o[1], 0, 0, 0);
;             }
; #pragma unroll
;             for (int j = 0; j < 8; ++j) S[j] = __builtin_amdgcn_mfma_f32_16x16x32_bf16(kf[j], vf, S[j] * dv[j], 0, 0, 0);
;             const int R0 = row0_of(chunk_of(s));
; #pragma unroll
;             for (int mt = 0; mt < 2; ++mt) { const int tr = 16 * mt + l15;
;                 u32x2 wv; wv.x = pk_bf16(o[mt][0] + bf_lo(oi[mt].x), o[mt][1] + bf_hi(oi[mt].x)); wv.y = pk_bf16(o[mt][2] + bf_lo(oi[mt].y), o[mt][3] + bf_hi(oi[mt].y));
;                 *(u32x2*)(OFBw + (size_t)h * PSLOT + (size_t)(R0 + tr) * 128 + vcol + 4 * q4) = wv; }
;             asm volatile("s_waitcnt lgkmcnt(0)" ::: "memory");
.LBB0_385:
	s_mul_i32 s6, s1, 0xab
	s_bfe_u32 s6, s6, 0x6000a
	s_mul_i32 s6, s6, 6
	s_sub_i32 s6, s1, s6
	s_and_b32 s6, s6, 0xff
	s_mulk_i32 s6, 0x6200
	s_add_i32 s6, s6, 16
	v_add_u32_e32 v34, s6, v55
	v_add_u32_e32 v35, v34, v63
	ds_read_b128 v[68:71], v35
	ds_read_b128 v[72:75], v35 offset:4096
	v_add_u32_e32 v35, v34, v64
	v_add_u32_e32 v84, s6, v58
	ds_read_b128 v[76:79], v35
	ds_read_b128 v[80:83], v35 offset:4096
	v_add_u32_e32 v35, v34, v65
	v_add_u32_e32 v34, v34, v66
	v_add3_u32 v67, s6, v56, v57
	v_add3_u32 v84, v84, v59, v60
	ds_read_b128 v[46:49], v35
	ds_read_b128 v[42:45], v35 offset:4096
	ds_read_b128 v[38:41], v34
	ds_read_b128 v[34:37], v34 offset:4096
	ds_read2st64_b64 v[84:87], v84 offset0:40 offset1:44
	v_add_u32_e32 v128, s6, v61
	v_add3_u32 v129, s6, v62, v57
	ds_read_b128 v[88:91], v67 offset:16384
	ds_read_b128 v[92:95], v128 offset:24576
	ds_read_b128 v[96:99], v128 offset:24640
	ds_read_b128 v[100:103], v128 offset:24704
	ds_read_b128 v[104:107], v129 offset:9216
	ds_read_b128 v[108:111], v129 offset:10240
	ds_read_b128 v[112:115], v128 offset:24768
	ds_read_b128 v[116:119], v128 offset:24832
	ds_read_b128 v[120:123], v129 offset:11264
	ds_read_b128 v[124:127], v129 offset:12288
	ds_read_b128 v[140:143], v128 offset:24896
	ds_read_b128 v[144:147], v128 offset:24960
	ds_read_b128 v[148:151], v129 offset:13312
	ds_read_b128 v[152:155], v129 offset:14336
	ds_read_b128 v[156:159], v129 offset:8192
	ds_read_b128 v[160:163], v128 offset:25024
	ds_read_b128 v[164:167], v129 offset:15360
	v_cvt_pk_bf16_f32 v168, v0, v1
	v_cvt_pk_bf16_f32 v169, v2, v3
	v_cvt_pk_bf16_f32 v170, v4, v5
	v_cvt_pk_bf16_f32 v171, v6, v7
	v_cvt_pk_bf16_f32 v172, v10, v11
	v_cvt_pk_bf16_f32 v173, v12, v13
	v_cvt_pk_bf16_f32 v174, v14, v15
	v_cvt_pk_bf16_f32 v175, v16, v17
	s_waitcnt lgkmcnt(14)
	v_mfma_f32_16x16x32_bf16 v[68:71], v[168:171], v[68:71], 0
	v_cvt_pk_bf16_f32 v188, v18, v19
	v_cvt_pk_bf16_f32 v189, v20, v21
	v_cvt_pk_bf16_f32 v190, v22, v23
	v_mfma_f32_16x16x32_bf16 v[72:75], v[168:171], v[72:75], 0
	v_cvt_pk_bf16_f32 v191, v24, v25
	s_cmp_gt_u32 s1, 7
	s_cselect_b32 s6, 0x8f, 7
	v_mfma_f32_16x16x32_bf16 v[68:71], v[172:175], v[76:79], v[68:71]
	v_cvt_pk_bf16_f32 v192, v26, v27
	v_cvt_pk_bf16_f32 v193, v28, v29
	v_cvt_pk_bf16_f32 v194, v30, v31
	v_mfma_f32_16x16x32_bf16 v[72:75], v[172:175], v[80:83], v[72:75]
	v_cvt_pk_bf16_f32 v195, v32, v33
	s_add_i32 s8, s6, s0
	s_and_b64 s[6:7], s[10:11], exec
	v_mfma_f32_16x16x32_bf16 v[46:49], v[188:191], v[46:49], v[68:71]
	s_cselect_b32 s6, s1, s8
	s_cmp_lt_i32 s6, 8
	v_lshl_or_b32 v67, s6, 5, v54
	v_mfma_f32_16x16x32_bf16 v[42:45], v[188:191], v[42:45], v[72:75]
	s_cselect_b32 s6, 8, 12
	s_cselect_b32 s7, 0x8000, s91
	s_lshl_b32 s6, s9, s6
	v_mfma_f32_16x16x32_bf16 v[38:41], v[192:195], v[38:41], v[46:49]
	s_add_i32 s6, s6, s7
	v_add_u32_e32 v68, s6, v67
	v_pk_mul_f32 v[0:1], v[0:1], v[92:93]
	v_mfma_f32_16x16x32_bf16 v[34:37], v[192:195], v[34:37], v[42:45]
	v_mul_f32_e64 v2, v2, v94
	v_mul_f32_e64 v3, v3, v95
	v_pk_mul_f32 v[4:5], v[4:5], v[96:97]
	v_pk_mul_f32 v[6:7], v[6:7], v[98:99]
	s_waitcnt lgkmcnt(13)
	v_pk_mul_f32 v[10:11], v[10:11], v[100:101]
	v_pk_mul_f32 v[12:13], v[12:13], v[102:103]
	s_waitcnt lgkmcnt(10)
	v_pk_mul_f32 v[14:15], v[14:15], v[112:113]
	v_pk_mul_f32 v[16:17], v[16:17], v[114:115]
	s_waitcnt lgkmcnt(9)
	v_pk_mul_f32 v[18:19], v[18:19], v[116:117]
	v_pk_mul_f32 v[20:21], v[20:21], v[118:119]
	s_waitcnt lgkmcnt(6)
	v_pk_mul_f32 v[22:23], v[22:23], v[140:141]
	v_pk_mul_f32 v[24:25], v[24:25], v[142:143]
	s_waitcnt lgkmcnt(5)
	v_pk_mul_f32 v[26:27], v[26:27], v[144:145]
	v_pk_mul_f32 v[28:29], v[28:29], v[146:147]
	s_waitcnt lgkmcnt(1)
	v_pk_mul_f32 v[30:31], v[30:31], v[160:161]
	v_pk_mul_f32 v[32:33], v[32:33], v[162:163]
	v_lshlrev_b32_e32 v92, 16, v84
	v_and_b32_e32 v93, 0xffff0000, v84
	v_lshlrev_b32_e32 v84, 16, v85
	v_and_b32_e32 v85, 0xffff0000, v85
	v_ashrrev_i32_e32 v69, 31, v68
	v_or_b32_e32 v70, 16, v68
	v_mfma_f32_16x16x32_bf16 v[0:3], v[156:159], v[88:91], v[0:3]
	v_lshlrev_b64 v[68:69], 8, v[68:69]
	v_ashrrev_i32_e32 v71, 31, v70
	v_pk_add_f32 v[38:39], v[38:39], v[92:93]
	v_mfma_f32_16x16x32_bf16 v[4:7], v[104:107], v[88:91], v[4:7]
	v_add_f32_e64 v40, v40, v84
	v_add_f32_e64 v41, v41, v85
	v_lshl_add_u64 v[46:47], v[50:51], 0, v[68:69]
	v_lshlrev_b64 v[48:49], 8, v[70:71]
	v_mfma_f32_16x16x32_bf16 v[10:13], v[108:111], v[88:91], v[10:13]
	v_cvt_pk_bf16_f32 v84, v38, v39
	v_cvt_pk_bf16_f32 v85, v40, v41
	v_lshl_add_u64 v[48:49], v[50:51], 0, v[48:49]
	v_mfma_f32_16x16x32_bf16 v[14:17], v[120:123], v[88:91], v[14:17]
	s_add_i32 s1, s1, 1
	s_add_i32 s0, s0, -1
	s_cmpk_eq_i32 s0, 0xff78
	v_mfma_f32_16x16x32_bf16 v[18:21], v[124:127], v[88:91], v[18:21]
	v_mfma_f32_16x16x32_bf16 v[22:25], v[148:151], v[88:91], v[22:25]
	v_mfma_f32_16x16x32_bf16 v[26:29], v[152:155], v[88:91], v[26:29]
	s_waitcnt lgkmcnt(0)
	v_mfma_f32_16x16x32_bf16 v[30:33], v[164:167], v[88:91], v[30:33]
	v_lshlrev_b32_e32 v88, 16, v86
	v_and_b32_e32 v89, 0xffff0000, v86
	v_lshlrev_b32_e32 v86, 16, v87
	v_and_b32_e32 v87, 0xffff0000, v87
	v_pk_add_f32 v[34:35], v[34:35], v[88:89]
	v_pk_add_f32 v[36:37], v[36:37], v[86:87]
	v_cvt_pk_bf16_f32 v86, v34, v35
	v_cvt_pk_bf16_f32 v87, v36, v37
	v_add_co_u32_e32 v48, vcc, -8, v48
	v_addc_co_u32_e32 v49, vcc, -1, v49, vcc
	s_mov_b32 vcc_lo, 0xffff0000
	s_mov_b32 vcc_hi, 0xffff0000
	s_nop 1
	v_cndmask_b32_e32 v46, v46, v48, vcc
	v_cndmask_b32_e32 v47, v47, v49, vcc
	v_permlane16_swap_b32_e32 v84, v86
	v_permlane16_swap_b32_e32 v85, v87
	global_store_dwordx4 v[46:47], v[84:87], off
	s_waitcnt lgkmcnt(0)
	s_barrier
	s_cbranch_scc0 .LBB0_385
	s_mov_b64 s[0:1], 0
; #define LAS __attribute__((address_space(3)))
; __device__ __forceinline__ size_t PIX(int row, int col) { return (size_t)(col >> 7) * PSLOT + (size_t)row * 128 + (col & 127); }
; __device__ void scan_chain(const Params& p, int l, int chain, int vhalf, LAS unsigned char* lds) {
;     ...
;         const int lw = w - 4;
;         const int r16 = lane >> 4, s16 = lane & 15;
;         size_t qoff[2], koff[2];
; #pragma unroll
;         for (int i = 0; i < 2; ++i) { const int row = 8 * lw + 4 * i + r16; qoff[i] = (size_t)row * qpitch + ((s16 ^ (row & 15)) * 8);
;             koff[i] = PIX(4 * (2 * lw + i) + r16, dir * 512 + h * 128) + s16 * 8; }
;         const size_t voff = PIX(16 * vhalf + 4 * lw + r16, 1024 + h * 128) + s16 * 8;
;         const float* dsrc = (const float*)(p.ws + WS_DS) + (size_t)chain * NCH * 128 + (lw & 1) * 64 + lane;
;         const int orow = 8 * lw + (lane >> 3);
;         const size_t ooff = (size_t)h * PSLOT + (size_t)orow * 128 + 64 * vhalf + (((lane & 7) ^ (orow & 7)) * 8);
;         const bf16_t* OFBc = (const bf16_t*)(p.ws + WS_OFB) + (size_t)dir * NROW * 512;
;         auto issue = [&](int s) {
;             const int sc = s < NCH ? s : NCH - 1;
;             const int c = chunk_of(sc), R0 = row0_of(c);
;             LAS unsigned char* st = lds + (s % NSTAGE) * ST_BYTES;
;             const bf16_t* qrow = qb + (size_t)R0 * qpitch; const bf16_t* krow = P + (size_t)R0 * 128;
; #pragma unroll
;             for (int i = 0; i < 2; ++i) {
;                 __builtin_amdgcn_global_load_lds((const unsigned*)(qrow + qoff[i]), (LAS unsigned*)(st + ST_Q + (2 * lw + i) * 1024), 16, 0, 0);
;                 __builtin_amdgcn_global_load_lds((const unsigned*)(krow + koff[i]), (LAS unsigned*)(st + ST_K + (2 * lw + i) * 1024), 16, 0, 0);
;             }
;             __builtin_amdgcn_global_load_lds((const unsigned*)(krow + voff), (LAS unsigned*)(st + ST_V + lw * 1024), 16, 0, 0);
;             __builtin_amdgcn_global_load_lds((const unsigned*)(dsrc + (size_t)c * 128), (LAS unsigned*)(st + ST_D + (lw & 1) * 256), 4, 0, 0);
;             __builtin_amdgcn_global_load_lds((const unsigned*)(OFBc + (size_t)R0 * 128 + ooff), (LAS unsigned*)(st + ST_O + lw * 1024), 16, 0, 0);
;         };
;         issue(0); issue(1); issue(2); issue(3); issue(4);
.LBB0_387:
	s_and_b64 vcc, exec, s[0:1]
	s_cbranch_vccz .LBB0_391
	s_add_i32 s6, s2, -4
	s_lshl_b32 s7, s6, 3
	v_or_b32_e32 v4, s7, v53
	v_mov_b32_e32 v5, v8
	v_lshlrev_b32_e32 v12, 3, v54
	v_readlane_b32 s0, v241, 48
	v_lshlrev_b64 v[2:3], 7, v[4:5]
	v_bitop3_b32 v0, s7, v9, v53 bitop3:0x36
	v_or_b32_e32 v10, 4, v4
	v_mov_b32_e32 v11, v8
	v_bitop3_b32 v4, v4, v9, 4 bitop3:0x36
	v_or_b32_e32 v6, s0, v12
	v_lshlrev_b32_e32 v0, 3, v0
	s_movk_i32 s0, 0x78
	v_lshlrev_b64 v[10:11], 7, v[10:11]
	v_lshlrev_b32_e32 v4, 3, v4
	v_and_or_b32 v0, v0, s0, v2
	v_and_or_b32 v4, v4, s0, v10
	s_lshl_b32 s0, s6, 2
	v_readlane_b32 s1, v242, 12
	v_mov_b32_e32 v7, v8
	s_add_i32 s0, s0, s1
	v_mov_b32_e32 v1, v3
	v_lshl_add_u64 v[2:3], v[2:3], 0, v[6:7]
	v_mov_b32_e32 v5, v11
	v_lshl_add_u64 v[6:7], v[10:11], 0, v[6:7]
	v_or_b32_e32 v10, s0, v53
	v_mov_b32_e32 v11, v8
	v_readlane_b32 s0, v241, 49
	v_lshlrev_b64 v[10:11], 7, v[10:11]
	v_readlane_b32 s1, v241, 50
	v_mov_b32_e32 v13, v8
	v_lshrrev_b32_e32 v16, 3, v52
	v_lshl_add_u64 v[10:11], v[10:11], 0, s[0:1]
	s_and_b32 s0, s5, 64
	s_lshl_b32 s0, s0, 2
	v_readlane_b32 s1, v242, 14
	s_add_u32 s0, s1, s0
	v_readlane_b32 s1, v242, 16
	v_or_b32_e32 v10, v10, v12
	s_addc_u32 s1, s1, 0
	v_lshlrev_b32_e32 v12, 2, v52
	v_lshl_add_u64 v[12:13], s[0:1], 0, v[12:13]
	v_or_b32_e32 v14, s7, v16
	v_mov_b32_e32 v15, v8
	v_readlane_b32 s0, v241, 51
	v_lshlrev_b64 v[14:15], 7, v[14:15]
	v_readlane_b32 s1, v241, 52
	v_readlane_b32 s10, v241, 26
	v_readlane_b32 s11, v241, 27
	v_lshl_add_u64 v[24:25], v[14:15], 0, s[0:1]
	s_lshl_b32 s0, s6, 11
	v_lshlrev_b64 v[14:15], 1, v[0:1]
	s_add_i32 s7, s0, 16
	v_bitop3_b32 v9, v16, v9, 7 bitop3:0x78
	v_lshl_add_u64 v[16:17], s[10:11], 0, v[14:15]
	s_mov_b32 m0, s7
	v_readlane_b32 s12, v242, 19
	global_load_lds_dwordx4 v[16:17], off
	v_lshlrev_b64 v[16:17], 1, v[2:3]
	v_readlane_b32 s13, v242, 20
	s_add_i32 s8, s7, 0x2000
	s_mov_b32 m0, s8
	v_lshl_add_u64 v[18:19], s[12:13], 0, v[16:17]
	global_load_lds_dwordx4 v[18:19], off
	v_lshlrev_b64 v[18:19], 1, v[4:5]
	s_add_i32 s9, s7, 0x400
	v_lshl_add_u64 v[20:21], s[10:11], 0, v[18:19]
	s_mov_b32 m0, s9
	s_add_i32 s10, s7, 0x2400
	global_load_lds_dwordx4 v[20:21], off
	v_lshlrev_b64 v[20:21], 1, v[6:7]
	v_lshl_add_u64 v[22:23], s[12:13], 0, v[20:21]
	s_mov_b32 m0, s10
	s_lshl_b32 s1, s6, 10
	global_load_lds_dwordx4 v[22:23], off
	v_lshlrev_b64 v[22:23], 1, v[10:11]
	s_add_i32 s6, s1, 16
	s_lshl_b32 s2, s2, 8
	v_lshl_add_u64 v[26:27], s[12:13], 0, v[22:23]
	s_add_i32 s11, s6, 0x4000
	v_readlane_b32 s12, v241, 53
	s_and_b32 s5, s2, 0x100
	s_mov_b32 m0, s11
	v_readlane_b32 s13, v241, 54
	s_add_i32 s2, s5, 16
	v_lshl_or_b32 v24, v9, 3, v24
	global_load_lds_dwordx4 v[26:27], off
	v_lshl_add_u64 v[26:27], v[12:13], 0, s[12:13]
	s_add_i32 s12, s2, 0x6000
	v_readlane_b32 s14, v242, 21
	s_mov_b32 m0, s12
	v_lshlrev_b64 v[24:25], 1, v[24:25]
	v_readlane_b32 s15, v242, 22
	s_add_i32 s13, s6, 0x5000
	v_readlane_b32 s16, v241, 28
	global_load_lds_dword v[26:27], off
	v_lshl_add_u64 v[26:27], s[14:15], 0, v[24:25]
	s_mov_b32 m0, s13
	v_readlane_b32 s17, v241, 29
	s_add_i32 s14, s7, 0x6200
	v_readlane_b32 s18, v242, 25
	global_load_lds_dwordx4 v[26:27], off
	v_lshl_add_u64 v[26:27], s[16:17], 0, v[14:15]
	s_mov_b32 m0, s14
	v_readlane_b32 s19, v242, 26
	s_add_i32 s15, s7, 0x8200
	global_load_lds_dwordx4 v[26:27], off
	v_lshl_add_u64 v[26:27], s[18:19], 0, v[16:17]
	s_mov_b32 m0, s15
	v_readlane_b32 s20, v241, 55
	global_load_lds_dwordx4 v[26:27], off
	v_lshl_add_u64 v[26:27], s[16:17], 0, v[18:19]
	s_add_i32 s16, s7, 0x6600
	s_mov_b32 m0, s16
	s_add_i32 s17, s7, 0x8600
	global_load_lds_dwordx4 v[26:27], off
	v_lshl_add_u64 v[26:27], s[18:19], 0, v[20:21]
	s_mov_b32 m0, s17
	v_readlane_b32 s21, v241, 56
	global_load_lds_dwordx4 v[26:27], off
	v_lshl_add_u64 v[26:27], s[18:19], 0, v[22:23]
	s_add_i32 s18, s6, 0xa200
	s_mov_b32 m0, s18
	s_add_i32 s19, s2, 0xc200
	global_load_lds_dwordx4 v[26:27], off
	v_lshl_add_u64 v[26:27], v[12:13], 0, s[20:21]
	v_readlane_b32 s20, v242, 27
	s_mov_b32 m0, s19
	v_readlane_b32 s21, v242, 28
	global_load_lds_dword v[26:27], off
	s_nop 0
	v_lshl_add_u64 v[26:27], s[20:21], 0, v[24:25]
	s_add_i32 s20, s6, 0xb200
	v_readlane_b32 s38, v241, 30
	s_mov_b32 m0, s20
	v_readlane_b32 s39, v241, 31
	v_readlane_b32 s22, v242, 29
	global_load_lds_dwordx4 v[26:27], off
	v_lshl_add_u64 v[26:27], s[38:39], 0, v[14:15]
	s_add_i32 m0, s7, 0xc400
	v_readlane_b32 s23, v242, 30
	global_load_lds_dwordx4 v[26:27], off
	s_nop 0
	v_lshl_add_u64 v[26:27], s[22:23], 0, v[16:17]
	s_add_i32 m0, s7, 0xe400
	s_nop 0
	global_load_lds_dwordx4 v[26:27], off
	v_lshl_add_u64 v[26:27], s[38:39], 0, v[18:19]
	s_add_i32 m0, s7, 0xc800
	v_readlane_b32 s38, v241, 32
	global_load_lds_dwordx4 v[26:27], off
	v_lshl_add_u64 v[26:27], s[22:23], 0, v[20:21]
	s_add_i32 m0, s7, 0xe800
	v_readlane_b32 s39, v241, 33
	global_load_lds_dwordx4 v[26:27], off
	v_lshl_add_u64 v[26:27], s[22:23], 0, v[22:23]
	v_readlane_b32 s22, v241, 57
	s_add_i32 m0, s6, 0x10400
	v_readlane_b32 s23, v241, 58
	global_load_lds_dwordx4 v[26:27], off
	s_nop 0
	v_lshl_add_u64 v[26:27], v[12:13], 0, s[22:23]
	v_readlane_b32 s22, v242, 31
	s_add_i32 m0, s2, 0x12400
	v_readlane_b32 s23, v242, 32
	global_load_lds_dword v[26:27], off
	s_nop 0
	v_lshl_add_u64 v[26:27], s[22:23], 0, v[24:25]
	s_add_i32 m0, s6, 0x11400
	v_readlane_b32 s22, v242, 33
	global_load_lds_dwordx4 v[26:27], off
	v_lshl_add_u64 v[26:27], s[38:39], 0, v[14:15]
	s_add_i32 m0, s7, 0x12600
	v_readlane_b32 s23, v242, 34
	global_load_lds_dwordx4 v[26:27], off
	s_nop 0
	v_lshl_add_u64 v[26:27], s[22:23], 0, v[16:17]
	s_add_i32 m0, s7, 0x14600
; #define LAS __attribute__((address_space(3)))
; __device__ void scan_chain(const Params& p, int l, int chain, int vhalf, LAS unsigned char* lds) {
;     ...
;         auto issue = [&](int s) {
;             const int sc = s < NCH ? s : NCH - 1;
;             const int c = chunk_of(sc), R0 = row0_of(c);
;             LAS unsigned char* st = lds + (s % NSTAGE) * ST_BYTES;
;             const bf16_t* qrow = qb + (size_t)R0 * qpitch; const bf16_t* krow = P + (size_t)R0 * 128;
; #pragma unroll
;             for (int i = 0; i < 2; ++i) {
;                 __builtin_amdgcn_global_load_lds((const unsigned*)(qrow + qoff[i]), (LAS unsigned*)(st + ST_Q + (2 * lw + i) * 1024), 16, 0, 0);
;                 __builtin_amdgcn_global_load_lds((const unsigned*)(krow + koff[i]), (LAS unsigned*)(st + ST_K + (2 * lw + i) * 1024), 16, 0, 0);
;             }
;             __builtin_amdgcn_global_load_lds((const unsigned*)(krow + voff), (LAS unsigned*)(st + ST_V + lw * 1024), 16, 0, 0);
;             __builtin_amdgcn_global_load_lds((const unsigned*)(dsrc + (size_t)c * 128), (LAS unsigned*)(st + ST_D + (lw & 1) * 256), 4, 0, 0);
;             __builtin_amdgcn_global_load_lds((const unsigned*)(OFBc + (size_t)R0 * 128 + ooff), (LAS unsigned*)(st + ST_O + lw * 1024), 16, 0, 0);
;         };
;         issue(0); issue(1); issue(2); issue(3); issue(4);
;         asm volatile("s_waitcnt vmcnt(28)" ::: "memory");
;         __builtin_amdgcn_s_barrier();
;         for (int s = 0; s < NCH; ++s) {
;             issue(s + 5);
;             asm volatile("s_waitcnt vmcnt(28)" ::: "memory");
;             __builtin_amdgcn_s_barrier();
;         }
	s_nop 0
	global_load_lds_dwordx4 v[26:27], off
	v_lshl_add_u64 v[26:27], s[38:39], 0, v[18:19]
	s_add_i32 m0, s7, 0x12a00
	v_readlane_b32 s38, v241, 34
	global_load_lds_dwordx4 v[26:27], off
	v_lshl_add_u64 v[26:27], s[22:23], 0, v[20:21]
	s_add_i32 m0, s7, 0x14a00
	v_readlane_b32 s39, v241, 35
	global_load_lds_dwordx4 v[26:27], off
	v_lshl_add_u64 v[26:27], s[22:23], 0, v[22:23]
	v_readlane_b32 s22, v241, 59
	s_add_i32 m0, s6, 0x16600
	v_readlane_b32 s23, v241, 60
	global_load_lds_dwordx4 v[26:27], off
	s_nop 0
	v_lshl_add_u64 v[26:27], v[12:13], 0, s[22:23]
	v_readlane_b32 s22, v242, 35
	s_add_i32 m0, s2, 0x18600
	v_readlane_b32 s23, v242, 36
	global_load_lds_dword v[26:27], off
	s_nop 0
	v_lshl_add_u64 v[26:27], s[22:23], 0, v[24:25]
	s_add_i32 m0, s6, 0x17600
	v_readlane_b32 s22, v242, 37
	global_load_lds_dwordx4 v[26:27], off
	v_lshl_add_u64 v[26:27], s[38:39], 0, v[14:15]
	s_add_i32 m0, s7, 0x18800
	v_readlane_b32 s23, v242, 38
	global_load_lds_dwordx4 v[26:27], off
	s_nop 0
	v_lshl_add_u64 v[26:27], s[22:23], 0, v[16:17]
	s_add_i32 m0, s7, 0x1a800
	s_nop 0
	global_load_lds_dwordx4 v[26:27], off
	v_lshl_add_u64 v[26:27], s[38:39], 0, v[18:19]
	s_add_i32 m0, s7, 0x18c00
	v_readlane_b32 s38, v241, 36
	global_load_lds_dwordx4 v[26:27], off
	v_lshl_add_u64 v[26:27], s[22:23], 0, v[20:21]
	s_add_i32 m0, s7, 0x1ac00
	v_readlane_b32 s39, v241, 37
	global_load_lds_dwordx4 v[26:27], off
	v_lshl_add_u64 v[26:27], s[22:23], 0, v[22:23]
	v_readlane_b32 s22, v241, 61
	s_add_i32 m0, s6, 0x1c800
	v_readlane_b32 s23, v241, 62
	global_load_lds_dwordx4 v[26:27], off
	s_nop 0
	v_lshl_add_u64 v[26:27], v[12:13], 0, s[22:23]
	v_readlane_b32 s22, v242, 41
	s_add_i32 m0, s2, 0x1e800
	v_readlane_b32 s23, v242, 42
	global_load_lds_dword v[26:27], off
	s_nop 0
	v_lshl_add_u64 v[26:27], s[22:23], 0, v[24:25]
	v_readlane_b32 s22, v242, 39
	v_readlane_b32 s23, v242, 40
	s_add_i32 m0, s6, 0x1d800
	s_nop 0
	v_lshl_add_u64 v[24:25], s[22:23], 0, v[24:25]
	v_readlane_b32 s22, v242, 45
	global_load_lds_dwordx4 v[26:27], off
	v_lshl_add_u64 v[26:27], s[38:39], 0, v[14:15]
	s_add_i32 m0, s7, 0x1ea00
	v_readlane_b32 s23, v242, 46
	s_waitcnt vmcnt(28)
	s_barrier
	global_load_lds_dwordx4 v[26:27], off
	v_lshl_add_u64 v[26:27], s[22:23], 0, v[16:17]
	s_add_i32 m0, s7, 0x20a00
	s_nop 0
	global_load_lds_dwordx4 v[26:27], off
	v_lshl_add_u64 v[26:27], s[38:39], 0, v[18:19]
	s_add_i32 m0, s7, 0x1ee00
	s_nop 0
	global_load_lds_dwordx4 v[26:27], off
	v_lshl_add_u64 v[26:27], s[22:23], 0, v[20:21]
	s_add_i32 m0, s7, 0x20e00
	s_nop 0
	global_load_lds_dwordx4 v[26:27], off
	v_lshl_add_u64 v[26:27], s[22:23], 0, v[22:23]
	v_readlane_b32 s22, v241, 63
	s_add_i32 m0, s6, 0x22a00
	v_readlane_b32 s23, v240, 0
	global_load_lds_dwordx4 v[26:27], off
	s_nop 0
	v_lshl_add_u64 v[26:27], v[12:13], 0, s[22:23]
	v_readlane_b32 s22, v242, 43
	s_add_i32 m0, s2, 0x24a00
	v_readlane_b32 s23, v242, 44
	global_load_lds_dword v[26:27], off
	s_nop 0
	v_lshl_add_u64 v[26:27], s[22:23], 1, v[24:25]
	s_add_i32 m0, s6, 0x23a00
	v_readlane_b32 s22, v241, 38
	global_load_lds_dwordx4 v[26:27], off
	v_readlane_b32 s23, v241, 39
	s_mov_b32 m0, s7
	v_readlane_b32 s6, v242, 49
	v_lshl_add_u64 v[26:27], s[22:23], 0, v[14:15]
	v_readlane_b32 s7, v242, 50
	s_waitcnt vmcnt(28)
	s_barrier
	global_load_lds_dwordx4 v[26:27], off
	v_lshl_add_u64 v[26:27], s[6:7], 0, v[16:17]
	s_mov_b32 m0, s8
	s_nop 0
	global_load_lds_dwordx4 v[26:27], off
	v_lshl_add_u64 v[26:27], s[22:23], 0, v[18:19]
	s_mov_b32 m0, s9
	v_readlane_b32 s8, v241, 42
	global_load_lds_dwordx4 v[26:27], off
	v_lshl_add_u64 v[26:27], s[6:7], 0, v[20:21]
	s_mov_b32 m0, s10
	v_readlane_b32 s9, v241, 43
	global_load_lds_dwordx4 v[26:27], off
	v_lshl_add_u64 v[26:27], s[6:7], 0, v[22:23]
	v_readlane_b32 s6, v240, 1
	s_mov_b32 m0, s11
	v_readlane_b32 s7, v240, 2
	global_load_lds_dwordx4 v[26:27], off
	s_nop 0
	v_lshl_add_u64 v[26:27], v[12:13], 0, s[6:7]
	v_readlane_b32 s6, v242, 47
	s_mov_b32 m0, s12
	v_readlane_b32 s7, v242, 48
	global_load_lds_dword v[26:27], off
	s_nop 0
	v_lshl_add_u64 v[26:27], s[6:7], 1, v[24:25]
	s_mov_b32 m0, s13
	v_readlane_b32 s6, v242, 53
	global_load_lds_dwordx4 v[26:27], off
	v_lshl_add_u64 v[14:15], s[8:9], 0, v[14:15]
	s_mov_b32 m0, s14
	v_readlane_b32 s7, v242, 54
	s_waitcnt vmcnt(28)
	s_barrier
	global_load_lds_dwordx4 v[14:15], off
	v_lshl_add_u64 v[14:15], s[6:7], 0, v[16:17]
	s_mov_b32 m0, s15
	v_readlane_b32 s14, v242, 23
	global_load_lds_dwordx4 v[14:15], off
	v_lshl_add_u64 v[14:15], s[8:9], 0, v[18:19]
	s_mov_b32 m0, s16
	v_readlane_b32 s12, v242, 17
	global_load_lds_dwordx4 v[14:15], off
	v_lshl_add_u64 v[14:15], s[6:7], 0, v[20:21]
	s_mov_b32 m0, s17
	v_readlane_b32 s15, v242, 24
	global_load_lds_dwordx4 v[14:15], off
	v_lshl_add_u64 v[14:15], s[6:7], 0, v[22:23]
	v_readlane_b32 s6, v240, 3
	s_mov_b32 m0, s18
	v_readlane_b32 s7, v240, 4
	global_load_lds_dwordx4 v[14:15], off
	s_nop 0
	v_lshl_add_u64 v[14:15], v[12:13], 0, s[6:7]
	v_readlane_b32 s6, v242, 51
	s_mov_b32 m0, s19
	v_readlane_b32 s7, v242, 52
	global_load_lds_dword v[14:15], off
	s_nop 0
	v_lshl_add_u64 v[14:15], s[6:7], 1, v[24:25]
	s_mov_b32 m0, s20
	s_mov_b32 s6, 8
	global_load_lds_dwordx4 v[14:15], off
	s_waitcnt vmcnt(28)
	v_readlane_b32 s13, v241, 40
	v_readlane_b32 s16, v241, 41
	s_barrier
	s_mov_b64 s[100:101], exec
	s_cmp_lt_u32 s1, 0x800
	s_cbranch_scc1 .Lscan_dm
	s_mov_b64 s[100:101], 1
; #define LAS __attribute__((address_space(3)))
; __device__ void scan_chain(const Params& p, int l, int chain, int vhalf, LAS unsigned char* lds) {
;     ...
;             __builtin_amdgcn_global_load_lds((const unsigned*)(dsrc + (size_t)c * 128), (LAS unsigned*)(st + ST_D + (lw & 1) * 256), 4, 0, 0);
;     ...
;         for (int s = 0; s < NCH; ++s) {
;             issue(s + 5);
;             asm volatile("s_waitcnt vmcnt(28)" ::: "memory");
;             __builtin_amdgcn_s_barrier();
;         }
;         asm volatile("s_waitcnt vmcnt(0)" ::: "memory");
.Lscan_dm:
.LBB0_389:
	s_min_u32 s2, s6, 0x87
	s_sub_i32 s7, 0x8f, s2
	s_and_b64 s[8:9], s[14:15], exec
	s_cselect_b32 s2, s2, s7
	s_lshl_b32 s7, s2, 5
	s_cmp_lt_u32 s2, 8
	s_cselect_b32 s8, 8, 12
	s_cselect_b32 s9, 0x8000, s91
	s_and_b32 s10, s6, 0xff
	s_lshl_b32 s8, s12, s8
	s_add_i32 s7, s9, s7
	s_mulk_i32 s10, 0xab
	s_add_i32 s8, s7, s8
	s_lshr_b32 s7, s10, 10
	s_mul_i32 s7, s7, 6
	s_sub_i32 s7, s6, s7
	s_and_b32 s7, s7, 0xff
	s_ashr_i32 s9, s8, 31
	s_mulk_i32 s7, 0x6200
	s_lshl_b64 s[8:9], s[8:9], 8
	s_add_i32 s7, s7, 16
	s_add_u32 s10, s13, s8
	s_addc_u32 s11, s16, s9
	v_lshl_add_u64 v[14:15], v[24:25], 0, s[8:9]
	s_add_u32 s8, s82, s8
	v_lshl_add_u64 v[16:17], v[0:1], 1, s[10:11]
	v_lshl_add_u64 v[18:19], v[4:5], 1, s[10:11]
	s_addc_u32 s9, s83, s9
	s_add_i32 s10, s7, s0
	s_mov_b32 m0, s10
	v_lshl_add_u64 v[20:21], v[2:3], 1, s[8:9]
	global_load_lds_dwordx4 v[16:17], off
	s_add_i32 m0, s10, 0x2000
	s_add_i32 s11, s7, s1
	global_load_lds_dwordx4 v[20:21], off
	s_add_i32 m0, s10, 0x400
	v_lshl_add_u64 v[22:23], v[6:7], 1, s[8:9]
	global_load_lds_dwordx4 v[18:19], off
	s_add_i32 m0, s10, 0x2400
	s_lshl_b32 s2, s2, 9
	s_add_i32 s7, s7, s5
	v_lshl_add_u64 v[26:27], v[10:11], 1, s[8:9]
	global_load_lds_dwordx4 v[22:23], off
	s_add_i32 m0, s11, 0x4000
	v_lshl_add_u64 v[28:29], v[12:13], 0, s[2:3]
	global_load_lds_dwordx4 v[26:27], off
	s_add_i32 m0, s7, 0x6000
	s_add_i32 s6, s6, 1
	s_mov_b64 s[98:99], exec
	s_mov_b64 exec, s[100:101]
	global_load_lds_dword v[28:29], off
	s_mov_b64 exec, s[98:99]
	s_add_i32 m0, s11, 0x5000
	s_cmpk_eq_i32 s6, 0x8d
	global_load_lds_dwordx4 v[14:15], off
	s_waitcnt vmcnt(28)
	s_barrier
	s_cbranch_scc0 .LBB0_389
	s_waitcnt vmcnt(0)
	v_readlane_b32 s14, v244, 49
	v_readlane_b32 s16, v244, 51
	v_readlane_b32 s12, v244, 53
	v_readlane_b32 s15, v244, 50
	v_readlane_b32 s17, v244, 52
	v_readlane_b32 s13, v244, 54
